# hyena pass C (both variants): per-position loads hoisted ahead of the store chain, waits recounted, guard wait at hoist point
# speedup vs baseline: 1.0705x; 1.0043x over previous
.LBB0_749:
	s_or_b64 exec, exec, s[42:43]
	v_add_u32_e32 v0, s21, v0
	v_mov_b64_e32 v[2:3], s[6:7]
	v_ashrrev_i32_e32 v1, 31, v0
	v_mad_i64_i32 v[2:3], s[22:23], v0, s0, v[2:3]
	s_mov_b64 s[22:23], 0x3000
	v_lshlrev_b64 v[0:1], 12, v[0:1]
	v_lshl_add_u64 v[22:23], v[2:3], 0, s[22:23]
	v_lshl_add_u64 v[0:1], s[30:31], 0, v[0:1]
	s_mov_b64 s[22:23], 0xcc00c00
	v_lshl_add_u64 v[20:21], v[0:1], 0, s[22:23]
	s_mov_b64 s[22:23], 0x2800
	v_lshl_add_u64 v[28:29], v[104:105], 0, s[22:23]
	v_lshl_add_u64 v[0:1], v[28:29], 0, s[70:71]
	s_waitcnt lgkmcnt(0)
	s_barrier
	global_load_dwordx4 v[0:3], v[0:1], off
	v_lshl_add_u64 v[26:27], v[106:107], 0, s[22:23]
	v_lshl_add_u64 v[24:25], v[108:109], 0, s[22:23]
	s_add_u32 s44, s46, 0x2000
	s_addc_u32 s45, s47, 0
	s_add_u32 s42, s46, 0x3800
	s_addc_u32 s43, s47, 0
	v_lshl_add_u64 v[30:31], v[20:21], 0, s[70:71]
	s_waitcnt vmcnt(1)
	v_lshl_add_u64 v[204:205], v[26:27], 0, s[70:71]
	global_load_dwordx4 v[206:209], v[204:205], off
	v_lshl_add_u64 v[210:211], v[24:25], 0, s[70:71]
	global_load_dwordx4 v[212:215], v[210:211], off
	v_lshl_add_u64 v[216:217], v[22:23], 0, s[70:71]
	global_load_dwordx4 v[218:221], v[216:217], off
	global_load_dwordx4 v[222:225], v161, s[48:49] offset:2064
	global_load_dwordx4 v[48:51], v161, s[48:49] offset:2048
	global_load_dwordx4 v[226:229], v161, s[46:47] offset:2064
	global_load_dwordx4 v[52:55], v161, s[46:47] offset:2048
	global_load_dwordx4 v[230:233], v161, s[44:45] offset:16
	global_load_dwordx4 v[56:59], v196, s[46:47]
	global_load_dwordx4 v[234:237], v161, s[42:43] offset:16
	global_load_dwordx4 v[238:241], v197, s[46:47] offset:2048
	s_waitcnt vmcnt(11)
	v_cndmask_b32_e64 v6, 0, v1, s[36:37]
	v_cndmask_b32_e64 v7, 0, v0, s[36:37]
	s_nop 0
	v_cndmask_b32_e64 v4, 0, v3, s[36:37]
	v_cndmask_b32_e64 v5, 0, v2, s[36:37]
	s_nop 0
	v_and_b32_e32 v13, 0xffff0000, v7
	v_lshlrev_b32_e32 v12, 16, v7
	v_and_b32_e32 v43, 0xffff0000, v6
	v_lshlrev_b32_e32 v42, 16, v6
	v_and_b32_e32 v39, 0xffff0000, v5
	v_lshlrev_b32_e32 v38, 16, v5
	v_and_b32_e32 v35, 0xffff0000, v4
	v_lshlrev_b32_e32 v34, 16, v4
	s_waitcnt vmcnt(10)
	v_cndmask_b32_e64 v10, 0, v207, s[38:39]
	v_cndmask_b32_e64 v11, 0, v206, s[38:39]
	s_nop 0
	v_cndmask_b32_e64 v8, 0, v209, s[38:39]
	v_cndmask_b32_e64 v9, 0, v208, s[38:39]
	s_nop 0
	v_and_b32_e32 v17, 0xffff0000, v11
	v_lshlrev_b32_e32 v16, 16, v11
	v_and_b32_e32 v45, 0xffff0000, v10
	v_lshlrev_b32_e32 v44, 16, v10
	v_and_b32_e32 v41, 0xffff0000, v9
	v_lshlrev_b32_e32 v40, 16, v9
	v_and_b32_e32 v37, 0xffff0000, v8
	v_lshlrev_b32_e32 v36, 16, v8
	s_waitcnt vmcnt(9)
	v_cndmask_b32_e64 v64, 0, v213, s[40:41]
	v_cndmask_b32_e64 v60, 0, v212, s[40:41]
	s_nop 0
	v_cndmask_b32_e64 v46, 0, v215, s[40:41]
	v_cndmask_b32_e64 v47, 0, v214, s[40:41]
	s_nop 0
	s_nop 0
	s_nop 0
	s_nop 0
	s_nop 0
	s_nop 0
	s_lshl_b32 s70, s20, 1
	s_waitcnt vmcnt(5)
	v_pk_fma_f32 v[4:5], v[226:227], v[38:39], v[222:223]
	s_waitcnt vmcnt(4)
	v_pk_fma_f32 v[18:19], v[52:53], v[12:13], v[48:49]
	s_nop 0
	s_nop 0
	v_and_b32_e32 v49, 0xffff0000, v60
	v_lshlrev_b32_e32 v48, 16, v60
	v_pk_fma_f32 v[42:43], v[54:55], v[42:43], v[50:51]
	v_and_b32_e32 v9, 0xffff0000, v47
	v_lshlrev_b32_e32 v8, 16, v47
	v_pk_fma_f32 v[6:7], v[228:229], v[34:35], v[224:225]
	s_waitcnt vmcnt(3)
	v_pk_fma_f32 v[4:5], v[230:231], v[40:41], v[4:5]
	s_waitcnt vmcnt(2)
	v_pk_fma_f32 v[32:33], v[56:57], v[16:17], v[18:19]
	s_nop 0
	s_nop 0
	v_and_b32_e32 v56, 0xffff0000, v218
	v_lshlrev_b32_e32 v0, 16, v218
	v_pk_fma_f32 v[42:43], v[58:59], v[44:45], v[42:43]
	v_and_b32_e32 v45, 0xffff0000, v64
	v_lshlrev_b32_e32 v44, 16, v64
	v_pk_fma_f32 v[6:7], v[232:233], v[36:37], v[6:7]
	s_waitcnt vmcnt(1)
	v_pk_fma_f32 v[4:5], v[234:235], v[8:9], v[4:5]
	s_waitcnt vmcnt(0)
	v_pk_fma_f32 v[32:33], v[238:239], v[48:49], v[32:33]
	ds_read_u16 v49, v82 offset:512
	ds_read_u16 v52, v82 offset:2048
	v_mul_f32_e32 v48, 0xbfb8aa3b, v0
	v_exp_f32_e32 v48, v48
	v_pk_fma_f32 v[42:43], v[240:241], v[44:45], v[42:43]
	v_and_b32_e32 v16, 0xffff0000, v220
	s_waitcnt lgkmcnt(0)
	v_lshlrev_b32_e32 v53, 16, v52
	v_lshlrev_b32_e32 v52, 16, v49
	v_mul_f32_e32 v49, 0xbfb8aa3b, v56
	v_exp_f32_e32 v49, v49
	v_pk_mul_f32 v[32:33], v[32:33], v[52:53]
	v_lshlrev_b32_e32 v2, 16, v220
	v_mul_f32_e32 v8, 0xbfb8aa3b, v2
	v_pk_add_f32 v[48:49], v[48:49], 1.0 op_sel_hi:[1,0]
	v_exp_f32_e32 v8, v8
	v_div_scale_f32 v52, s[22:23], v49, v49, v56
	v_rcp_f32_e32 v53, v52
	s_nop 0
	v_fma_f32 v57, -v52, v53, 1.0
	v_fmac_f32_e32 v53, v57, v53
	v_div_scale_f32 v57, vcc, v56, v49, v56
	v_mul_f32_e32 v60, v57, v53
	v_fma_f32 v61, -v52, v60, v57
	v_fmac_f32_e32 v60, v61, v53
	v_fma_f32 v52, -v52, v60, v57
	v_div_fmas_f32 v52, v52, v53, v60
	v_div_fixup_f32 v49, v52, v49, v56
	v_div_scale_f32 v52, s[22:23], v48, v48, v0
	v_rcp_f32_e32 v53, v52
	s_nop 0
	v_fma_f32 v56, -v52, v53, 1.0
	v_fmac_f32_e32 v53, v56, v53
	v_div_scale_f32 v56, vcc, v0, v48, v0
	v_mul_f32_e32 v57, v56, v53
	v_fma_f32 v60, -v52, v57, v56
	v_fmac_f32_e32 v57, v60, v53
	v_fma_f32 v52, -v52, v57, v56
	v_div_fmas_f32 v52, v52, v53, v57
	v_div_fixup_f32 v48, v52, v48, v0
	v_pk_mul_f32 v[32:33], v[48:49], v[32:33]
	v_and_b32_e32 v48, 0xffff0000, v219
	v_lshlrev_b32_e32 v49, 16, v219
	ds_read_u16 v1, v82 offset:3584
	ds_read_u16 v44, v82 offset:5120
	v_mul_f32_e32 v0, 0xbfb8aa3b, v49
	v_exp_f32_e32 v0, v0
	ds_read_u16 v9, v82 offset:6656
	ds_read_u16 v12, v82 offset:8192
	s_waitcnt lgkmcnt(2)
	v_lshlrev_b32_e32 v45, 16, v44
	v_lshlrev_b32_e32 v44, 16, v1
	v_mul_f32_e32 v1, 0xbfb8aa3b, v48
	v_exp_f32_e32 v1, v1
	v_pk_mul_f32 v[42:43], v[42:43], v[44:45]
	s_waitcnt lgkmcnt(0)
	v_lshlrev_b32_e32 v13, 16, v12
	v_lshlrev_b32_e32 v12, 16, v9
	v_pk_add_f32 v[0:1], v[0:1], 1.0 op_sel_hi:[1,0]
	v_mul_f32_e32 v9, 0xbfb8aa3b, v16
	v_div_scale_f32 v44, s[22:23], v1, v1, v48
	v_rcp_f32_e32 v45, v44
	v_exp_f32_e32 v9, v9
	v_pk_mul_f32 v[4:5], v[4:5], v[12:13]
	v_fma_f32 v50, -v44, v45, 1.0
	v_fmac_f32_e32 v45, v50, v45
	v_div_scale_f32 v50, vcc, v48, v1, v48
	v_mul_f32_e32 v51, v50, v45
	v_fma_f32 v52, -v44, v51, v50
	v_fmac_f32_e32 v51, v52, v45
	v_fma_f32 v44, -v44, v51, v50
	v_div_fmas_f32 v44, v44, v45, v51
	v_div_fixup_f32 v1, v44, v1, v48
	v_div_scale_f32 v44, s[22:23], v0, v0, v49
	v_rcp_f32_e32 v45, v44
	v_pk_add_f32 v[8:9], v[8:9], 1.0 op_sel_hi:[1,0]
	v_fma_f32 v48, -v44, v45, 1.0
	v_div_scale_f32 v12, s[22:23], v9, v9, v16
	v_fmac_f32_e32 v45, v48, v45
	v_div_scale_f32 v48, vcc, v49, v0, v49
	v_rcp_f32_e32 v13, v12
	v_mul_f32_e32 v50, v48, v45
	v_fma_f32 v51, -v44, v50, v48
	v_fmac_f32_e32 v50, v51, v45
	v_fma_f32 v44, -v44, v50, v48
	v_fma_f32 v17, -v12, v13, 1.0
	v_div_fmas_f32 v44, v44, v45, v50
	v_fmac_f32_e32 v13, v17, v13
	v_div_scale_f32 v17, vcc, v16, v9, v16
	v_mul_f32_e32 v38, v17, v13
	v_fma_f32 v39, -v12, v38, v17
	v_fmac_f32_e32 v38, v39, v13
	v_fma_f32 v12, -v12, v38, v17
	v_div_fmas_f32 v12, v12, v13, v38
	v_div_fixup_f32 v9, v12, v9, v16
	v_div_scale_f32 v12, s[22:23], v8, v8, v2
	v_rcp_f32_e32 v13, v12
	v_div_fixup_f32 v0, v44, v0, v49
	v_pk_mul_f32 v[0:1], v[0:1], v[42:43]
	v_fma_f32 v16, -v12, v13, 1.0
	v_fmac_f32_e32 v13, v16, v13
	v_div_scale_f32 v16, vcc, v2, v8, v2
	v_mul_f32_e32 v17, v16, v13
	v_fma_f32 v38, -v12, v17, v16
	v_fmac_f32_e32 v17, v38, v13
	v_fma_f32 v12, -v12, v17, v16
	v_div_fmas_f32 v12, v12, v13, v17
	v_div_fixup_f32 v8, v12, v8, v2
	v_pk_mul_f32 v[4:5], v[8:9], v[4:5]
	v_and_b32_e32 v9, 0xffff0000, v46
	v_lshlrev_b32_e32 v8, 16, v46
	v_pk_fma_f32 v[6:7], v[236:237], v[8:9], v[6:7]
	v_and_b32_e32 v9, 0xffff0000, v221
	v_lshlrev_b32_e32 v8, 16, v221
	ds_read_u16 v3, v82 offset:9728
	ds_read_u16 v10, v82 offset:11264
	v_mul_f32_e32 v2, 0xbfb8aa3b, v8
	v_exp_f32_e32 v2, v2
	s_waitcnt lgkmcnt(0)
	v_lshlrev_b32_e32 v11, 16, v10
	v_lshlrev_b32_e32 v10, 16, v3
	v_mul_f32_e32 v3, 0xbfb8aa3b, v9
	v_exp_f32_e32 v3, v3
	v_pk_mul_f32 v[6:7], v[6:7], v[10:11]
	v_pk_add_f32 v[2:3], v[2:3], 1.0 op_sel_hi:[1,0]
	s_nop 0
	v_div_scale_f32 v10, s[22:23], v3, v3, v9
	v_rcp_f32_e32 v11, v10
	s_nop 0
	v_fma_f32 v12, -v10, v11, 1.0
	v_fmac_f32_e32 v11, v12, v11
	v_div_scale_f32 v12, vcc, v9, v3, v9
	v_mul_f32_e32 v13, v12, v11
	v_fma_f32 v14, -v10, v13, v12
	v_fmac_f32_e32 v13, v14, v11
	v_fma_f32 v10, -v10, v13, v12
	v_div_fmas_f32 v10, v10, v11, v13
	v_div_fixup_f32 v3, v10, v3, v9
	v_div_scale_f32 v9, s[22:23], v2, v2, v8
	v_rcp_f32_e32 v10, v9
	s_nop 0
	v_fma_f32 v11, -v9, v10, 1.0
	v_fmac_f32_e32 v10, v11, v10
	v_div_scale_f32 v11, vcc, v8, v2, v8
	v_mul_f32_e32 v12, v11, v10
	v_fma_f32 v13, -v9, v12, v11
	v_fmac_f32_e32 v12, v13, v10
	v_fma_f32 v9, -v9, v12, v11
	v_div_fmas_f32 v9, v9, v10, v12
	v_div_fixup_f32 v2, v9, v2, v8
	v_pk_mul_f32 v[2:3], v[2:3], v[6:7]
	v_bfe_u32 v12, v33, 16, 1
	v_bfe_u32 v13, v32, 16, 1
	v_add3_u32 v13, v32, v13, s94
	v_add3_u32 v12, v33, v12, s94
	v_cvt_pk_bf16_f32 v0, v0, v1
	v_cvt_pk_bf16_f32 v4, v4, v5
	v_cvt_pk_bf16_f32 v2, v2, v3
	v_mov_b32_e32 v3, v2
	v_mov_b32_e32 v2, v4
	v_mov_b32_e32 v1, v0
	v_perm_b32 v0, v12, v13, s95
	global_store_dwordx4 v[30:31], v[0:3], off
	v_mov_b32_e32 v15, v233
	v_mov_b32_e32 v18, v236
	v_mov_b32_e32 v19, v237
	v_mov_b32_e32 v62, v240
	v_mov_b32_e32 v63, v241
	v_lshl_add_u64 v[30:31], v[20:21], 0, s[70:71]
	s_nop 0
	v_lshl_add_u64 v[0:1], v[28:29], 0, s[70:71]
	global_load_dwordx4 v[0:3], v[0:1], off
	s_waitcnt vmcnt(1)
	v_lshl_add_u64 v[204:205], v[26:27], 0, s[70:71]
	global_load_dwordx4 v[206:209], v[204:205], off
	v_lshl_add_u64 v[210:211], v[24:25], 0, s[70:71]
	global_load_dwordx4 v[212:215], v[210:211], off
	v_lshl_add_u64 v[216:217], v[22:23], 0, s[70:71]
	global_load_dwordx4 v[218:221], v[216:217], off
	global_load_dwordx4 v[222:225], v161, s[48:49] offset:2096
	global_load_dwordx4 v[18:21], v161, s[48:49] offset:2080
	global_load_dwordx4 v[226:229], v161, s[46:47] offset:2096
	global_load_dwordx4 v[22:25], v161, s[46:47] offset:2080
	global_load_dwordx4 v[26:29], v196, s[46:47] offset:32
	global_load_dwordx4 v[48:51], v197, s[46:47] offset:2080
	s_waitcnt vmcnt(9)
	v_cndmask_b32_e64 v6, 0, v1, s[36:37]
	v_cndmask_b32_e64 v7, 0, v0, s[36:37]
	s_nop 0
	v_cndmask_b32_e64 v4, 0, v3, s[36:37]
	v_cndmask_b32_e64 v5, 0, v2, s[36:37]
	s_nop 0
	v_and_b32_e32 v13, 0xffff0000, v7
	v_lshlrev_b32_e32 v12, 16, v7
	v_and_b32_e32 v41, 0xffff0000, v6
	v_lshlrev_b32_e32 v40, 16, v6
	v_and_b32_e32 v37, 0xffff0000, v5
	v_lshlrev_b32_e32 v36, 16, v5
	v_and_b32_e32 v33, 0xffff0000, v4
	v_lshlrev_b32_e32 v32, 16, v4
	s_waitcnt vmcnt(8)
	v_cndmask_b32_e64 v10, 0, v207, s[38:39]
	v_cndmask_b32_e64 v11, 0, v206, s[38:39]
	s_nop 0
	v_cndmask_b32_e64 v8, 0, v209, s[38:39]
	v_cndmask_b32_e64 v9, 0, v208, s[38:39]
	s_nop 0
	v_and_b32_e32 v17, 0xffff0000, v11
	v_lshlrev_b32_e32 v16, 16, v11
	v_and_b32_e32 v43, 0xffff0000, v10
	v_lshlrev_b32_e32 v42, 16, v10
	v_and_b32_e32 v39, 0xffff0000, v9
	v_lshlrev_b32_e32 v38, 16, v9
	v_and_b32_e32 v35, 0xffff0000, v8
	v_lshlrev_b32_e32 v34, 16, v8
	s_add_u32 s38, s46, 0x2020
	s_addc_u32 s39, s47, 0
	s_add_u32 s36, s46, 0x3820
	s_addc_u32 s37, s47, 0
	s_waitcnt vmcnt(7)
	v_cndmask_b32_e64 v46, 0, v213, s[40:41]
	v_cndmask_b32_e64 v47, 0, v212, s[40:41]
	s_nop 0
	v_cndmask_b32_e64 v44, 0, v215, s[40:41]
	v_cndmask_b32_e64 v45, 0, v214, s[40:41]
	s_nop 0
	s_nop 0
	s_nop 0
	s_nop 0
	s_nop 0
	s_nop 0
	s_waitcnt vmcnt(3)
	v_pk_fma_f32 v[4:5], v[226:227], v[36:37], v[222:223]
	s_waitcnt vmcnt(2)
	v_pk_fma_f32 v[18:19], v[22:23], v[12:13], v[18:19]
	global_load_dwordx4 v[12:15], v161, s[38:39] offset:16
	s_nop 0
	v_pk_fma_f32 v[20:21], v[24:25], v[40:41], v[20:21]
	v_and_b32_e32 v25, 0xffff0000, v46
	v_lshlrev_b32_e32 v24, 16, v46
	v_and_b32_e32 v9, 0xffff0000, v45
	v_lshlrev_b32_e32 v8, 16, v45
	v_pk_fma_f32 v[6:7], v[228:229], v[32:33], v[224:225]
	s_waitcnt vmcnt(0)
	v_pk_fma_f32 v[4:5], v[12:13], v[38:39], v[4:5]
	v_pk_fma_f32 v[22:23], v[26:27], v[16:17], v[18:19]
	global_load_dwordx4 v[16:19], v161, s[36:37] offset:16
	s_nop 0
	v_and_b32_e32 v27, 0xffff0000, v47
	v_lshlrev_b32_e32 v26, 16, v47
	v_and_b32_e32 v47, 0xffff0000, v218
	v_lshlrev_b32_e32 v0, 16, v218
	v_pk_fma_f32 v[20:21], v[28:29], v[42:43], v[20:21]
	v_pk_fma_f32 v[6:7], v[14:15], v[34:35], v[6:7]
	s_waitcnt vmcnt(0)
	v_pk_fma_f32 v[4:5], v[16:17], v[8:9], v[4:5]
	v_pk_fma_f32 v[22:23], v[48:49], v[26:27], v[22:23]
	ds_read_u16 v27, v82 offset:12800
	ds_read_u16 v48, v82 offset:14336
	v_mul_f32_e32 v26, 0xbfb8aa3b, v0
	v_exp_f32_e32 v26, v26
	v_pk_fma_f32 v[20:21], v[50:51], v[24:25], v[20:21]
	v_and_b32_e32 v16, 0xffff0000, v220
	s_waitcnt lgkmcnt(0)
	v_lshlrev_b32_e32 v49, 16, v48
	v_lshlrev_b32_e32 v48, 16, v27
	v_mul_f32_e32 v27, 0xbfb8aa3b, v47
	v_exp_f32_e32 v27, v27
	v_pk_mul_f32 v[22:23], v[22:23], v[48:49]
	v_lshlrev_b32_e32 v2, 16, v220
	v_mul_f32_e32 v8, 0xbfb8aa3b, v2
	v_pk_add_f32 v[26:27], v[26:27], 1.0 op_sel_hi:[1,0]
	v_exp_f32_e32 v8, v8
	v_div_scale_f32 v48, s[20:21], v27, v27, v47
	v_rcp_f32_e32 v49, v48
	s_nop 0
	v_fma_f32 v52, -v48, v49, 1.0
	v_fmac_f32_e32 v49, v52, v49
	v_div_scale_f32 v52, vcc, v47, v27, v47
	v_mul_f32_e32 v53, v52, v49
	v_fma_f32 v54, -v48, v53, v52
	v_fmac_f32_e32 v53, v54, v49
	v_fma_f32 v48, -v48, v53, v52
	v_div_fmas_f32 v48, v48, v49, v53
	v_div_fixup_f32 v27, v48, v27, v47
	v_div_scale_f32 v47, s[20:21], v26, v26, v0
	v_rcp_f32_e32 v48, v47
	s_nop 0
	v_fma_f32 v49, -v47, v48, 1.0
	v_fmac_f32_e32 v48, v49, v48
	v_div_scale_f32 v49, vcc, v0, v26, v0
	v_mul_f32_e32 v52, v49, v48
	v_fma_f32 v53, -v47, v52, v49
	v_fmac_f32_e32 v52, v53, v48
	v_fma_f32 v47, -v47, v52, v49
	v_div_fmas_f32 v47, v47, v48, v52
	v_div_fixup_f32 v26, v47, v26, v0
	v_pk_mul_f32 v[22:23], v[26:27], v[22:23]
	v_and_b32_e32 v26, 0xffff0000, v219
	v_lshlrev_b32_e32 v27, 16, v219
	ds_read_u16 v1, v82 offset:15872
	ds_read_u16 v24, v82 offset:17408
	v_mul_f32_e32 v0, 0xbfb8aa3b, v27
	v_exp_f32_e32 v0, v0
	ds_read_u16 v9, v82 offset:18944
	ds_read_u16 v12, v82 offset:20480
	s_waitcnt lgkmcnt(2)
	v_lshlrev_b32_e32 v25, 16, v24
	v_lshlrev_b32_e32 v24, 16, v1
	v_mul_f32_e32 v1, 0xbfb8aa3b, v26
	v_exp_f32_e32 v1, v1
	v_pk_mul_f32 v[20:21], v[20:21], v[24:25]
	s_waitcnt lgkmcnt(0)
	v_lshlrev_b32_e32 v13, 16, v12
	v_lshlrev_b32_e32 v12, 16, v9
	v_pk_add_f32 v[0:1], v[0:1], 1.0 op_sel_hi:[1,0]
	v_mul_f32_e32 v9, 0xbfb8aa3b, v16
	v_div_scale_f32 v24, s[20:21], v1, v1, v26
	v_rcp_f32_e32 v25, v24
	v_exp_f32_e32 v9, v9
	v_pk_mul_f32 v[4:5], v[4:5], v[12:13]
	v_fma_f32 v28, -v24, v25, 1.0
	v_fmac_f32_e32 v25, v28, v25
	v_div_scale_f32 v28, vcc, v26, v1, v26
	v_mul_f32_e32 v29, v28, v25
	v_fma_f32 v40, -v24, v29, v28
	v_fmac_f32_e32 v29, v40, v25
	v_fma_f32 v24, -v24, v29, v28
	v_div_fmas_f32 v24, v24, v25, v29
	v_div_fixup_f32 v1, v24, v1, v26
	v_div_scale_f32 v24, s[20:21], v0, v0, v27
	v_rcp_f32_e32 v25, v24
	v_pk_add_f32 v[8:9], v[8:9], 1.0 op_sel_hi:[1,0]
	v_fma_f32 v26, -v24, v25, 1.0
	v_fmac_f32_e32 v25, v26, v25
	v_div_scale_f32 v26, vcc, v27, v0, v27
	v_div_scale_f32 v12, s[20:21], v9, v9, v16
	v_mul_f32_e32 v28, v26, v25
	v_rcp_f32_e32 v13, v12
	v_fma_f32 v29, -v24, v28, v26
	v_fmac_f32_e32 v28, v29, v25
	v_fma_f32 v24, -v24, v28, v26
	v_div_fmas_f32 v24, v24, v25, v28
	v_fma_f32 v17, -v12, v13, 1.0
	v_div_fixup_f32 v0, v24, v0, v27
	v_fmac_f32_e32 v13, v17, v13
	v_div_scale_f32 v17, vcc, v16, v9, v16
	v_pk_mul_f32 v[0:1], v[0:1], v[20:21]
	v_mul_f32_e32 v20, v17, v13
	v_fma_f32 v21, -v12, v20, v17
	v_fmac_f32_e32 v20, v21, v13
	v_fma_f32 v12, -v12, v20, v17
	v_div_fmas_f32 v12, v12, v13, v20
	v_div_fixup_f32 v9, v12, v9, v16
	v_div_scale_f32 v12, s[20:21], v8, v8, v2
	v_rcp_f32_e32 v13, v12
	s_nop 0
	v_fma_f32 v16, -v12, v13, 1.0
	v_fmac_f32_e32 v13, v16, v13
	v_div_scale_f32 v16, vcc, v2, v8, v2
	v_mul_f32_e32 v17, v16, v13
	v_fma_f32 v20, -v12, v17, v16
	v_fmac_f32_e32 v17, v20, v13
	v_fma_f32 v12, -v12, v17, v16
	v_div_fmas_f32 v12, v12, v13, v17
	v_div_fixup_f32 v8, v12, v8, v2
	v_pk_mul_f32 v[4:5], v[8:9], v[4:5]
	v_and_b32_e32 v9, 0xffff0000, v44
	v_lshlrev_b32_e32 v8, 16, v44
	v_pk_fma_f32 v[6:7], v[18:19], v[8:9], v[6:7]
	v_and_b32_e32 v9, 0xffff0000, v221
	v_lshlrev_b32_e32 v8, 16, v221
	ds_read_u16 v3, v82 offset:22016
	ds_read_u16 v10, v82 offset:23552
	v_mul_f32_e32 v2, 0xbfb8aa3b, v8
	v_exp_f32_e32 v2, v2
	s_waitcnt lgkmcnt(0)
	v_lshlrev_b32_e32 v11, 16, v10
	v_lshlrev_b32_e32 v10, 16, v3
	v_mul_f32_e32 v3, 0xbfb8aa3b, v9
	v_exp_f32_e32 v3, v3
	v_pk_mul_f32 v[6:7], v[6:7], v[10:11]
	v_pk_add_f32 v[2:3], v[2:3], 1.0 op_sel_hi:[1,0]
	s_nop 0
	v_div_scale_f32 v10, s[20:21], v3, v3, v9
	v_rcp_f32_e32 v11, v10
	s_nop 0
	v_fma_f32 v12, -v10, v11, 1.0
	v_fmac_f32_e32 v11, v12, v11
	v_div_scale_f32 v12, vcc, v9, v3, v9
	v_mul_f32_e32 v13, v12, v11
	v_fma_f32 v14, -v10, v13, v12
	v_fmac_f32_e32 v13, v14, v11
	v_fma_f32 v10, -v10, v13, v12
	v_div_fmas_f32 v10, v10, v11, v13
	v_div_fixup_f32 v3, v10, v3, v9
	v_div_scale_f32 v9, s[20:21], v2, v2, v8
	v_rcp_f32_e32 v10, v9
	s_nop 0
	v_fma_f32 v11, -v9, v10, 1.0
	v_fmac_f32_e32 v10, v11, v10
	v_div_scale_f32 v11, vcc, v8, v2, v8
	v_mul_f32_e32 v12, v11, v10
	v_fma_f32 v13, -v9, v12, v11
	v_fmac_f32_e32 v12, v13, v10
	v_fma_f32 v9, -v9, v12, v11
	v_div_fmas_f32 v9, v9, v10, v12
	v_div_fixup_f32 v2, v9, v2, v8
	v_pk_mul_f32 v[2:3], v[2:3], v[6:7]
	v_bfe_u32 v12, v23, 16, 1
	v_bfe_u32 v13, v22, 16, 1
	v_add3_u32 v13, v22, v13, s94
	v_add3_u32 v12, v23, v12, s94
	v_cvt_pk_bf16_f32 v0, v0, v1
	v_cvt_pk_bf16_f32 v4, v4, v5
	v_cvt_pk_bf16_f32 v2, v2, v3
	v_mov_b32_e32 v3, v2
	v_mov_b32_e32 v2, v4
	v_mov_b32_e32 v1, v0
	v_perm_b32 v0, v12, v13, s95
	global_store_dwordx4 v[30:31], v[0:3], off
	s_barrier

.LBB0_838:
	s_or_b64 exec, exec, s[42:43]
	v_lshl_add_u64 v[2:3], v[94:95], 0, s[70:71]
	v_add_co_u32_e32 v2, vcc, 0x2000, v2
	s_waitcnt lgkmcnt(0)
	s_nop 0
	v_addc_co_u32_e32 v3, vcc, 0, v3, vcc
	s_barrier
	global_load_dwordx4 v[2:5], v[2:3], off offset:2048
	v_add_u32_e32 v34, s19, v0
	v_mov_b64_e32 v[36:37], s[6:7]
	v_mad_i64_i32 v[0:1], s[20:21], v34, s0, v[36:37]
	v_lshl_add_u64 v[0:1], v[0:1], 0, s[70:71]
	s_movk_i32 s23, 0x3000
	v_ashrrev_i32_e32 v35, 31, v34
	s_mov_b32 s22, 0xcc00000
	v_readlane_b32 s88, v253, 36
	v_readlane_b32 s89, v253, 37
	s_waitcnt vmcnt(1)
	v_lshl_add_u64 v[206:207], v[96:97], 0, s[70:71]
	v_add_co_u32_e32 v206, vcc, s3, v206
	s_nop 1
	v_addc_co_u32_e32 v207, vcc, 0, v207, vcc
	global_load_dwordx4 v[208:211], v[206:207], off offset:2048
	v_lshl_add_u64 v[214:215], v[98:99], 0, s[70:71]
	v_add_co_u32_e32 v214, vcc, s3, v214
	s_nop 1
	v_addc_co_u32_e32 v215, vcc, 0, v215, vcc
	global_load_dwordx4 v[216:219], v[214:215], off offset:2048
	v_add_co_u32_e32 v0, vcc, s23, v0
	s_nop 1
	v_addc_co_u32_e32 v1, vcc, 0, v1, vcc
	global_load_dwordx4 v[220:223], v[0:1], off
	global_load_dwordx4 v[224:227], v161, s[84:85] offset:2064
	global_load_dwordx4 v[18:21], v161, s[84:85] offset:2048
	global_load_dwordx4 v[228:231], v161, s[86:87] offset:2064
	global_load_dwordx4 v[22:25], v161, s[86:87] offset:2048
	global_load_dwordx4 v[26:29], v196, s[86:87]
	global_load_dwordx4 v[232:235], v197, s[86:87] offset:2048
	s_waitcnt vmcnt(9)
	v_cndmask_b32_e64 v8, 0, v3, s[36:37]
	v_cndmask_b32_e64 v9, 0, v2, s[36:37]
	s_nop 0
	s_nop 0
	v_cndmask_b32_e64 v6, 0, v5, s[36:37]
	s_nop 0
	s_nop 0
	v_cndmask_b32_e64 v7, 0, v4, s[36:37]
	s_nop 0
	v_and_b32_e32 v13, 0xffff0000, v9
	v_lshlrev_b32_e32 v12, 16, v9
	v_and_b32_e32 v47, 0xffff0000, v8
	v_lshlrev_b32_e32 v46, 16, v8
	v_and_b32_e32 v43, 0xffff0000, v7
	v_lshlrev_b32_e32 v42, 16, v7
	v_and_b32_e32 v39, 0xffff0000, v6
	v_lshlrev_b32_e32 v38, 16, v6
	s_add_u32 s36, s86, 0x2000
	s_addc_u32 s37, s87, 0
	s_waitcnt vmcnt(8)
	v_cndmask_b32_e64 v14, 0, v209, s[38:39]
	v_cndmask_b32_e64 v15, 0, v208, s[38:39]
	s_nop 0
	s_nop 0
	v_cndmask_b32_e64 v10, 0, v211, s[38:39]
	s_nop 0
	s_nop 0
	v_cndmask_b32_e64 v11, 0, v210, s[38:39]
	s_nop 0
	s_nop 0
	v_and_b32_e32 v45, 0xffff0000, v11
	s_nop 0
	s_nop 0
	v_lshlrev_b32_e32 v44, 16, v11
	v_and_b32_e32 v41, 0xffff0000, v10
	v_lshlrev_b32_e32 v40, 16, v10
	v_and_b32_e32 v17, 0xffff0000, v15
	v_lshlrev_b32_e32 v16, 16, v15
	v_and_b32_e32 v49, 0xffff0000, v14
	v_lshlrev_b32_e32 v48, 16, v14
	s_add_u32 s38, s86, 0x3800
	s_addc_u32 s39, s87, 0
	s_waitcnt vmcnt(7)
	v_cndmask_b32_e64 v50, 0, v219, s[40:41]
	v_cndmask_b32_e64 v51, 0, v218, s[40:41]
	v_cndmask_b32_e64 v52, 0, v217, s[40:41]
	v_cndmask_b32_e64 v30, 0, v216, s[40:41]
	s_nop 0
	s_nop 0
	s_nop 0
	s_nop 0
	s_nop 0
	s_nop 0
	s_waitcnt vmcnt(3)
	v_pk_fma_f32 v[4:5], v[228:229], v[42:43], v[224:225]
	s_waitcnt vmcnt(2)
	v_pk_fma_f32 v[18:19], v[22:23], v[12:13], v[18:19]
	global_load_dwordx4 v[12:15], v161, s[36:37] offset:16
	s_nop 0
	v_and_b32_e32 v53, 0xffff0000, v220
	v_lshlrev_b32_e32 v0, 16, v220
	v_pk_fma_f32 v[20:21], v[24:25], v[46:47], v[20:21]
	v_and_b32_e32 v25, 0xffff0000, v52
	v_lshlrev_b32_e32 v24, 16, v52
	v_and_b32_e32 v9, 0xffff0000, v51
	v_lshlrev_b32_e32 v8, 16, v51
	v_pk_fma_f32 v[6:7], v[230:231], v[38:39], v[226:227]
	v_and_b32_e32 v10, 0xffff0000, v223
	v_lshlrev_b32_e32 v11, 16, v223
	s_waitcnt vmcnt(0)
	v_pk_fma_f32 v[4:5], v[12:13], v[44:45], v[4:5]
	v_pk_fma_f32 v[22:23], v[26:27], v[16:17], v[18:19]
	v_and_b32_e32 v27, 0xffff0000, v30
	v_lshlrev_b32_e32 v26, 16, v30
	global_load_dwordx4 v[16:19], v161, s[38:39] offset:16
	s_nop 0
	v_pk_fma_f32 v[20:21], v[28:29], v[48:49], v[20:21]
	v_pk_fma_f32 v[6:7], v[14:15], v[40:41], v[6:7]
	s_waitcnt vmcnt(0)
	v_pk_fma_f32 v[4:5], v[16:17], v[8:9], v[4:5]
	v_pk_fma_f32 v[22:23], v[232:233], v[26:27], v[22:23]
	ds_read_u16 v27, v101 offset:512
	ds_read_u16 v30, v101 offset:3584
	v_mul_f32_e32 v26, 0xbfb8aa3b, v0
	v_exp_f32_e32 v26, v26
	v_pk_fma_f32 v[20:21], v[234:235], v[24:25], v[20:21]
	v_and_b32_e32 v16, 0xffff0000, v222
	s_waitcnt lgkmcnt(0)
	v_lshlrev_b32_e32 v31, 16, v30
	v_lshlrev_b32_e32 v30, 16, v27
	v_mul_f32_e32 v27, 0xbfb8aa3b, v53
	v_exp_f32_e32 v27, v27
	v_pk_mul_f32 v[22:23], v[22:23], v[30:31]
	v_lshlrev_b32_e32 v2, 16, v222
	v_mul_f32_e32 v8, 0xbfb8aa3b, v2
	v_pk_add_f32 v[26:27], v[26:27], 1.0 op_sel_hi:[1,0]
	v_exp_f32_e32 v8, v8
	v_div_scale_f32 v30, s[20:21], v27, v27, v53
	v_rcp_f32_e32 v31, v30
	s_nop 0
	v_fma_f32 v54, -v30, v31, 1.0
	v_fmac_f32_e32 v31, v54, v31
	v_div_scale_f32 v54, vcc, v53, v27, v53
	v_mul_f32_e32 v55, v54, v31
	v_fma_f32 v56, -v30, v55, v54
	v_fmac_f32_e32 v55, v56, v31
	v_fma_f32 v30, -v30, v55, v54
	v_div_fmas_f32 v30, v30, v31, v55
	v_div_fixup_f32 v27, v30, v27, v53
	v_div_scale_f32 v30, s[20:21], v26, v26, v0
	v_rcp_f32_e32 v31, v30
	s_nop 0
	v_fma_f32 v53, -v30, v31, 1.0
	v_fmac_f32_e32 v31, v53, v31
	v_div_scale_f32 v53, vcc, v0, v26, v0
	v_mul_f32_e32 v54, v53, v31
	v_fma_f32 v55, -v30, v54, v53
	v_fmac_f32_e32 v54, v55, v31
	v_fma_f32 v30, -v30, v54, v53
	v_div_fmas_f32 v30, v30, v31, v54
	v_div_fixup_f32 v26, v30, v26, v0
	v_pk_mul_f32 v[22:23], v[26:27], v[22:23]
	v_and_b32_e32 v26, 0xffff0000, v221
	v_lshlrev_b32_e32 v27, 16, v221
	ds_read_u16 v1, v101 offset:6656
	ds_read_u16 v24, v101 offset:9728
	v_mul_f32_e32 v0, 0xbfb8aa3b, v27
	v_exp_f32_e32 v0, v0
	ds_read_u16 v9, v101 offset:12800
	ds_read_u16 v12, v101 offset:15872
	s_waitcnt lgkmcnt(2)
	v_lshlrev_b32_e32 v25, 16, v24
	v_lshlrev_b32_e32 v24, 16, v1
	v_mul_f32_e32 v1, 0xbfb8aa3b, v26
	v_exp_f32_e32 v1, v1
	v_pk_mul_f32 v[20:21], v[20:21], v[24:25]
	s_waitcnt lgkmcnt(0)
	v_lshlrev_b32_e32 v13, 16, v12
	v_lshlrev_b32_e32 v12, 16, v9
	v_pk_add_f32 v[0:1], v[0:1], 1.0 op_sel_hi:[1,0]
	v_mul_f32_e32 v9, 0xbfb8aa3b, v16
	v_div_scale_f32 v24, s[20:21], v1, v1, v26
	v_rcp_f32_e32 v25, v24
	v_exp_f32_e32 v9, v9
	v_pk_mul_f32 v[4:5], v[4:5], v[12:13]
	v_fma_f32 v28, -v24, v25, 1.0
	v_fmac_f32_e32 v25, v28, v25
	v_div_scale_f32 v28, vcc, v26, v1, v26
	v_mul_f32_e32 v29, v28, v25
	v_fma_f32 v30, -v24, v29, v28
	v_fmac_f32_e32 v29, v30, v25
	v_fma_f32 v24, -v24, v29, v28
	v_div_fmas_f32 v24, v24, v25, v29
	v_div_fixup_f32 v1, v24, v1, v26
	v_div_scale_f32 v24, s[20:21], v0, v0, v27
	v_rcp_f32_e32 v25, v24
	v_pk_add_f32 v[8:9], v[8:9], 1.0 op_sel_hi:[1,0]
	v_fma_f32 v26, -v24, v25, 1.0
	v_fmac_f32_e32 v25, v26, v25
	v_div_scale_f32 v26, vcc, v27, v0, v27
	v_div_scale_f32 v12, s[20:21], v9, v9, v16
	v_mul_f32_e32 v28, v26, v25
	v_rcp_f32_e32 v13, v12
	v_fma_f32 v29, -v24, v28, v26
	v_fmac_f32_e32 v28, v29, v25
	v_fma_f32 v24, -v24, v28, v26
	v_div_fmas_f32 v24, v24, v25, v28
	v_fma_f32 v17, -v12, v13, 1.0
	v_div_fixup_f32 v0, v24, v0, v27
	v_fmac_f32_e32 v13, v17, v13
	v_div_scale_f32 v17, vcc, v16, v9, v16
	v_pk_mul_f32 v[0:1], v[0:1], v[20:21]
	v_mul_f32_e32 v20, v17, v13
	v_fma_f32 v21, -v12, v20, v17
	v_fmac_f32_e32 v20, v21, v13
	v_fma_f32 v12, -v12, v20, v17
	v_div_fmas_f32 v12, v12, v13, v20
	v_div_fixup_f32 v9, v12, v9, v16
	v_div_scale_f32 v12, s[20:21], v8, v8, v2
	v_rcp_f32_e32 v13, v12
	s_nop 0
	v_fma_f32 v16, -v12, v13, 1.0
	v_fmac_f32_e32 v13, v16, v13
	v_div_scale_f32 v16, vcc, v2, v8, v2
	v_mul_f32_e32 v17, v16, v13
	v_fma_f32 v20, -v12, v17, v16
	v_fmac_f32_e32 v17, v20, v13
	v_fma_f32 v12, -v12, v17, v16
	v_div_fmas_f32 v12, v12, v13, v17
	v_div_fixup_f32 v8, v12, v8, v2
	v_pk_mul_f32 v[4:5], v[8:9], v[4:5]
	v_and_b32_e32 v9, 0xffff0000, v50
	v_lshlrev_b32_e32 v8, 16, v50
	v_pk_fma_f32 v[6:7], v[18:19], v[8:9], v[6:7]
	ds_read_u16 v3, v101 offset:18944
	ds_read_u16 v8, v101 offset:22016
	v_mul_f32_e32 v2, 0xbfb8aa3b, v11
	v_exp_f32_e32 v2, v2
	s_waitcnt lgkmcnt(0)
	v_lshlrev_b32_e32 v9, 16, v8
	v_lshlrev_b32_e32 v8, 16, v3
	v_mul_f32_e32 v3, 0xbfb8aa3b, v10
	v_exp_f32_e32 v3, v3
	v_pk_mul_f32 v[6:7], v[6:7], v[8:9]
	v_pk_add_f32 v[2:3], v[2:3], 1.0 op_sel_hi:[1,0]
	s_nop 0
	v_div_scale_f32 v8, s[20:21], v3, v3, v10
	v_rcp_f32_e32 v9, v8
	s_nop 0
	v_fma_f32 v12, -v8, v9, 1.0
	v_fmac_f32_e32 v9, v12, v9
	v_div_scale_f32 v12, vcc, v10, v3, v10
	v_mul_f32_e32 v13, v12, v9
	v_fma_f32 v14, -v8, v13, v12
	v_fmac_f32_e32 v13, v14, v9
	v_fma_f32 v8, -v8, v13, v12
	v_div_fmas_f32 v8, v8, v9, v13
	v_div_fixup_f32 v3, v8, v3, v10
	v_div_scale_f32 v8, s[20:21], v2, v2, v11
	v_rcp_f32_e32 v9, v8
	s_nop 0
	v_fma_f32 v10, -v8, v9, 1.0
	v_fmac_f32_e32 v9, v10, v9
	v_div_scale_f32 v10, vcc, v11, v2, v11
	v_mul_f32_e32 v12, v10, v9
	v_fma_f32 v13, -v8, v12, v10
	v_fmac_f32_e32 v12, v13, v9
	v_fma_f32 v8, -v8, v12, v10
	v_div_fmas_f32 v8, v8, v9, v12
	v_div_fixup_f32 v2, v8, v2, v11
	v_pk_mul_f32 v[2:3], v[2:3], v[6:7]
	v_cvt_pk_bf16_f32 v4, v4, v5
	v_cvt_pk_bf16_f32 v2, v2, v3
	v_mov_b32_e32 v3, v2
	v_mov_b32_e32 v2, v4
	v_lshlrev_b64 v[4:5], 12, v[34:35]
	v_lshl_add_u64 v[4:5], s[30:31], 0, v[4:5]
	v_bfe_u32 v12, v23, 16, 1
	v_bfe_u32 v13, v22, 16, 1
	v_lshl_add_u64 v[4:5], v[4:5], 0, s[70:71]
	v_add3_u32 v13, v22, v13, s94
	v_add3_u32 v12, v23, v12, s94
	v_cvt_pk_bf16_f32 v0, v0, v1
	v_add_co_u32_e32 v4, vcc, s22, v4
	v_mov_b32_e32 v1, v0
	v_perm_b32 v0, v12, v13, s95
	v_addc_co_u32_e32 v5, vcc, 0, v5, vcc
	global_store_dwordx4 v[4:5], v[0:3], off offset:3072
	v_mov_b32_e32 v32, v234
	v_mov_b32_e32 v33, v235
	v_add_u32_e32 v34, s19, v124
	v_ashrrev_i32_e32 v35, 31, v34
	v_lshl_add_u64 v[0:1], v[110:111], 0, s[70:71]
	v_add_co_u32_e32 v0, vcc, s3, v0
	s_nop 1
	v_addc_co_u32_e32 v1, vcc, 0, v1, vcc
	global_load_dwordx4 v[0:3], v[0:1], off offset:2048
	s_waitcnt vmcnt(1)
	v_lshl_add_u64 v[206:207], v[114:115], 0, s[70:71]
	v_add_co_u32_e32 v206, vcc, s3, v206
	s_nop 1
	v_addc_co_u32_e32 v207, vcc, 0, v207, vcc
	global_load_dwordx4 v[208:211], v[206:207], off offset:2048
	v_lshl_add_u64 v[214:215], v[118:119], 0, s[70:71]
	v_add_co_u32_e32 v214, vcc, s3, v214
	s_nop 1
	v_addc_co_u32_e32 v215, vcc, 0, v215, vcc
	global_load_dwordx4 v[216:219], v[214:215], off offset:2048
	v_mad_i64_i32 v[222:223], s[20:21], v34, s0, v[36:37]
	v_lshl_add_u64 v[224:225], v[222:223], 0, s[70:71]
	v_add_co_u32_e32 v224, vcc, s23, v224
	s_nop 1
	v_addc_co_u32_e32 v225, vcc, 0, v225, vcc
	global_load_dwordx4 v[226:229], v[224:225], off
	global_load_dwordx4 v[230:233], v161, s[84:85] offset:2064
	global_load_dwordx4 v[18:21], v161, s[84:85] offset:2048
	global_load_dwordx4 v[234:237], v161, s[86:87] offset:2064
	global_load_dwordx4 v[22:25], v161, s[86:87] offset:2048
	global_load_dwordx4 v[238:241], v161, s[36:37] offset:16
	global_load_dwordx4 v[26:29], v196, s[86:87]
	global_load_dwordx4 v[242:245], v161, s[38:39] offset:16
	global_load_dwordx4 v[246:249], v197, s[86:87] offset:2048
	s_waitcnt vmcnt(11)
	v_cndmask_b32_e64 v6, 0, v1, s[50:51]
	v_cndmask_b32_e64 v7, 0, v0, s[50:51]
	s_nop 0
	s_nop 0
	v_cndmask_b32_e64 v4, 0, v3, s[50:51]
	s_nop 0
	s_nop 0
	v_cndmask_b32_e64 v5, 0, v2, s[50:51]
	s_nop 0
	v_and_b32_e32 v13, 0xffff0000, v7
	v_lshlrev_b32_e32 v12, 16, v7
	v_and_b32_e32 v47, 0xffff0000, v6
	v_lshlrev_b32_e32 v46, 16, v6
	v_and_b32_e32 v43, 0xffff0000, v5
	v_lshlrev_b32_e32 v42, 16, v5
	v_and_b32_e32 v39, 0xffff0000, v4
	v_lshlrev_b32_e32 v38, 16, v4
	s_waitcnt vmcnt(10)
	v_cndmask_b32_e64 v10, 0, v209, s[56:57]
	v_cndmask_b32_e64 v11, 0, v208, s[56:57]
	s_nop 0
	s_nop 0
	v_cndmask_b32_e64 v8, 0, v211, s[56:57]
	s_nop 0
	s_nop 0
	v_cndmask_b32_e64 v9, 0, v210, s[56:57]
	s_nop 0
	v_and_b32_e32 v17, 0xffff0000, v11
	v_lshlrev_b32_e32 v16, 16, v11
	v_and_b32_e32 v49, 0xffff0000, v10
	v_lshlrev_b32_e32 v48, 16, v10
	v_and_b32_e32 v45, 0xffff0000, v9
	v_lshlrev_b32_e32 v44, 16, v9
	v_and_b32_e32 v41, 0xffff0000, v8
	v_lshlrev_b32_e32 v40, 16, v8
	s_waitcnt vmcnt(9)
	v_cndmask_b32_e64 v52, 0, v217, s[60:61]
	v_cndmask_b32_e64 v30, 0, v216, s[60:61]
	s_nop 0
	s_nop 0
	s_nop 0
	v_cndmask_b32_e64 v50, 0, v219, s[60:61]
	s_nop 0
	s_nop 0
	v_cndmask_b32_e64 v51, 0, v218, s[60:61]
	s_nop 0
	s_nop 0
	s_nop 0
	s_nop 0
	s_nop 0
	s_nop 0
	s_waitcnt vmcnt(5)
	v_pk_fma_f32 v[4:5], v[234:235], v[42:43], v[230:231]
	s_waitcnt vmcnt(4)
	v_pk_fma_f32 v[18:19], v[22:23], v[12:13], v[18:19]
	s_nop 0
	s_nop 0
	v_pk_fma_f32 v[20:21], v[24:25], v[46:47], v[20:21]
	v_and_b32_e32 v25, 0xffff0000, v52
	v_lshlrev_b32_e32 v24, 16, v52
	v_and_b32_e32 v9, 0xffff0000, v51
	v_lshlrev_b32_e32 v8, 16, v51
	v_pk_fma_f32 v[6:7], v[236:237], v[38:39], v[232:233]
	v_and_b32_e32 v10, 0xffff0000, v229
	v_lshlrev_b32_e32 v11, 16, v229
	s_waitcnt vmcnt(3)
	v_pk_fma_f32 v[4:5], v[238:239], v[44:45], v[4:5]
	s_waitcnt vmcnt(2)
	v_pk_fma_f32 v[22:23], v[26:27], v[16:17], v[18:19]
	v_and_b32_e32 v27, 0xffff0000, v30
	v_lshlrev_b32_e32 v26, 16, v30
	s_nop 0
	s_nop 0
	v_pk_fma_f32 v[20:21], v[28:29], v[48:49], v[20:21]
	v_pk_fma_f32 v[6:7], v[240:241], v[40:41], v[6:7]
	s_waitcnt vmcnt(1)
	v_pk_fma_f32 v[4:5], v[242:243], v[8:9], v[4:5]
	s_waitcnt vmcnt(0)
	v_pk_fma_f32 v[22:23], v[246:247], v[26:27], v[22:23]
	ds_read_u16 v27, v101 offset:1024
	ds_read_u16 v31, v101 offset:4096
	v_and_b32_e32 v30, 0xffff0000, v226
	v_lshlrev_b32_e32 v0, 16, v226
	v_mul_f32_e32 v26, 0xbfb8aa3b, v0
	s_waitcnt lgkmcnt(1)
	v_lshlrev_b32_e32 v54, 16, v27
	v_mul_f32_e32 v27, 0xbfb8aa3b, v30
	v_exp_f32_e32 v26, v26
	v_exp_f32_e32 v27, v27
	s_waitcnt lgkmcnt(0)
	v_lshlrev_b32_e32 v55, 16, v31
	v_pk_mul_f32 v[22:23], v[22:23], v[54:55]
	v_pk_fma_f32 v[20:21], v[248:249], v[24:25], v[20:21]
	v_pk_add_f32 v[26:27], v[26:27], 1.0 op_sel_hi:[1,0]
	v_and_b32_e32 v16, 0xffff0000, v228
	v_div_scale_f32 v31, s[20:21], v27, v27, v30
	v_rcp_f32_e32 v53, v31
	v_lshlrev_b32_e32 v2, 16, v228
	v_mul_f32_e32 v8, 0xbfb8aa3b, v2
	v_exp_f32_e32 v8, v8
	v_fma_f32 v54, -v31, v53, 1.0
	v_fmac_f32_e32 v53, v54, v53
	v_div_scale_f32 v54, vcc, v30, v27, v30
	v_mul_f32_e32 v55, v54, v53
	v_fma_f32 v56, -v31, v55, v54
	v_fmac_f32_e32 v55, v56, v53
	v_fma_f32 v31, -v31, v55, v54
	v_div_fmas_f32 v31, v31, v53, v55
	v_div_fixup_f32 v27, v31, v27, v30
	v_div_scale_f32 v30, s[20:21], v26, v26, v0
	v_rcp_f32_e32 v31, v30
	s_nop 0
	v_fma_f32 v53, -v30, v31, 1.0
	v_fmac_f32_e32 v31, v53, v31
	v_div_scale_f32 v53, vcc, v0, v26, v0
	v_mul_f32_e32 v54, v53, v31
	v_fma_f32 v55, -v30, v54, v53
	v_fmac_f32_e32 v54, v55, v31
	v_fma_f32 v30, -v30, v54, v53
	v_div_fmas_f32 v30, v30, v31, v54
	v_div_fixup_f32 v26, v30, v26, v0
	v_pk_mul_f32 v[22:23], v[26:27], v[22:23]
	v_and_b32_e32 v26, 0xffff0000, v227
	v_lshlrev_b32_e32 v27, 16, v227
	ds_read_u16 v1, v101 offset:7168
	ds_read_u16 v24, v101 offset:10240
	v_mul_f32_e32 v0, 0xbfb8aa3b, v27
	v_exp_f32_e32 v0, v0
	ds_read_u16 v9, v101 offset:13312
	ds_read_u16 v12, v101 offset:16384
	s_waitcnt lgkmcnt(2)
	v_lshlrev_b32_e32 v25, 16, v24
	v_lshlrev_b32_e32 v24, 16, v1
	v_mul_f32_e32 v1, 0xbfb8aa3b, v26
	v_exp_f32_e32 v1, v1
	v_pk_mul_f32 v[20:21], v[20:21], v[24:25]
	s_waitcnt lgkmcnt(0)
	v_lshlrev_b32_e32 v13, 16, v12
	v_lshlrev_b32_e32 v12, 16, v9
	v_pk_add_f32 v[0:1], v[0:1], 1.0 op_sel_hi:[1,0]
	v_mul_f32_e32 v9, 0xbfb8aa3b, v16
	v_div_scale_f32 v24, s[20:21], v1, v1, v26
	v_rcp_f32_e32 v25, v24
	v_exp_f32_e32 v9, v9
	v_pk_mul_f32 v[4:5], v[4:5], v[12:13]
	v_fma_f32 v28, -v24, v25, 1.0
	v_fmac_f32_e32 v25, v28, v25
	v_div_scale_f32 v28, vcc, v26, v1, v26
	v_mul_f32_e32 v29, v28, v25
	v_fma_f32 v30, -v24, v29, v28
	v_fmac_f32_e32 v29, v30, v25
	v_fma_f32 v24, -v24, v29, v28
	v_div_fmas_f32 v24, v24, v25, v29
	v_div_fixup_f32 v1, v24, v1, v26
	v_div_scale_f32 v24, s[20:21], v0, v0, v27
	v_rcp_f32_e32 v25, v24
	v_pk_add_f32 v[8:9], v[8:9], 1.0 op_sel_hi:[1,0]
	v_fma_f32 v26, -v24, v25, 1.0
	v_fmac_f32_e32 v25, v26, v25
	v_div_scale_f32 v26, vcc, v27, v0, v27
	v_div_scale_f32 v12, s[20:21], v9, v9, v16
	v_mul_f32_e32 v28, v26, v25
	v_rcp_f32_e32 v13, v12
	v_fma_f32 v29, -v24, v28, v26
	v_fmac_f32_e32 v28, v29, v25
	v_fma_f32 v24, -v24, v28, v26
	v_div_fmas_f32 v24, v24, v25, v28
	v_fma_f32 v17, -v12, v13, 1.0
	v_div_fixup_f32 v0, v24, v0, v27
	v_fmac_f32_e32 v13, v17, v13
	v_div_scale_f32 v17, vcc, v16, v9, v16
	v_pk_mul_f32 v[0:1], v[0:1], v[20:21]
	v_mul_f32_e32 v20, v17, v13
	v_fma_f32 v21, -v12, v20, v17
	v_fmac_f32_e32 v20, v21, v13
	v_fma_f32 v12, -v12, v20, v17
	v_div_fmas_f32 v12, v12, v13, v20
	v_div_fixup_f32 v9, v12, v9, v16
	v_div_scale_f32 v12, s[20:21], v8, v8, v2
	v_rcp_f32_e32 v13, v12
	s_nop 0
	v_fma_f32 v16, -v12, v13, 1.0
	v_fmac_f32_e32 v13, v16, v13
	v_div_scale_f32 v16, vcc, v2, v8, v2
	v_mul_f32_e32 v17, v16, v13
	v_fma_f32 v20, -v12, v17, v16
	v_fmac_f32_e32 v17, v20, v13
	v_fma_f32 v12, -v12, v17, v16
	v_div_fmas_f32 v12, v12, v13, v17
	v_div_fixup_f32 v8, v12, v8, v2
	v_pk_mul_f32 v[4:5], v[8:9], v[4:5]
	v_and_b32_e32 v9, 0xffff0000, v50
	v_lshlrev_b32_e32 v8, 16, v50
	v_pk_fma_f32 v[6:7], v[244:245], v[8:9], v[6:7]
	ds_read_u16 v3, v101 offset:19456
	ds_read_u16 v8, v101 offset:22528
	v_mul_f32_e32 v2, 0xbfb8aa3b, v11
	v_exp_f32_e32 v2, v2
	s_waitcnt lgkmcnt(0)
	v_lshlrev_b32_e32 v9, 16, v8
	v_lshlrev_b32_e32 v8, 16, v3
	v_mul_f32_e32 v3, 0xbfb8aa3b, v10
	v_exp_f32_e32 v3, v3
	v_pk_mul_f32 v[6:7], v[6:7], v[8:9]
	v_pk_add_f32 v[2:3], v[2:3], 1.0 op_sel_hi:[1,0]
	s_nop 0
	v_div_scale_f32 v8, s[20:21], v3, v3, v10
	v_rcp_f32_e32 v9, v8
	s_nop 0
	v_fma_f32 v12, -v8, v9, 1.0
	v_fmac_f32_e32 v9, v12, v9
	v_div_scale_f32 v12, vcc, v10, v3, v10
	v_mul_f32_e32 v13, v12, v9
	v_fma_f32 v14, -v8, v13, v12
	v_fmac_f32_e32 v13, v14, v9
	v_fma_f32 v8, -v8, v13, v12
	v_div_fmas_f32 v8, v8, v9, v13
	v_div_fixup_f32 v3, v8, v3, v10
	v_div_scale_f32 v8, s[20:21], v2, v2, v11
	v_rcp_f32_e32 v9, v8
	s_nop 0
	v_fma_f32 v10, -v8, v9, 1.0
	v_fmac_f32_e32 v9, v10, v9
	v_div_scale_f32 v10, vcc, v11, v2, v11
	v_mul_f32_e32 v12, v10, v9
	v_fma_f32 v13, -v8, v12, v10
	v_fmac_f32_e32 v12, v13, v9
	v_fma_f32 v8, -v8, v12, v10
	v_div_fmas_f32 v8, v8, v9, v12
	v_div_fixup_f32 v2, v8, v2, v11
	v_pk_mul_f32 v[2:3], v[2:3], v[6:7]
	v_cvt_pk_bf16_f32 v4, v4, v5
	v_cvt_pk_bf16_f32 v2, v2, v3
	v_mov_b32_e32 v3, v2
	v_mov_b32_e32 v2, v4
	v_lshlrev_b64 v[4:5], 12, v[34:35]
	v_lshl_add_u64 v[4:5], s[30:31], 0, v[4:5]
	v_bfe_u32 v12, v23, 16, 1
	v_bfe_u32 v13, v22, 16, 1
	v_lshl_add_u64 v[4:5], v[4:5], 0, s[70:71]
	v_add3_u32 v13, v22, v13, s94
	v_add3_u32 v12, v23, v12, s94
	v_cvt_pk_bf16_f32 v0, v0, v1
	v_add_co_u32_e32 v4, vcc, s22, v4
	v_mov_b32_e32 v1, v0
	v_perm_b32 v0, v12, v13, s95
	v_addc_co_u32_e32 v5, vcc, 0, v5, vcc
	global_store_dwordx4 v[4:5], v[0:3], off offset:3072
	v_mov_b32_e32 v15, v241
	v_mov_b32_e32 v18, v244
	v_mov_b32_e32 v19, v245
	v_mov_b32_e32 v32, v248
	v_mov_b32_e32 v33, v249
	v_add_u32_e32 v34, s19, v123
	v_ashrrev_i32_e32 v35, 31, v34
	v_lshl_add_u64 v[0:1], v[108:109], 0, s[70:71]
	v_add_co_u32_e32 v0, vcc, s3, v0
	s_nop 1
	v_addc_co_u32_e32 v1, vcc, 0, v1, vcc
	global_load_dwordx4 v[0:3], v[0:1], off offset:2048
	s_waitcnt vmcnt(1)
	v_lshl_add_u64 v[206:207], v[112:113], 0, s[70:71]
	v_add_co_u32_e32 v206, vcc, s3, v206
	s_nop 1
	v_addc_co_u32_e32 v207, vcc, 0, v207, vcc
	global_load_dwordx4 v[208:211], v[206:207], off offset:2048
	v_lshl_add_u64 v[214:215], v[116:117], 0, s[70:71]
	v_add_co_u32_e32 v214, vcc, s3, v214
	s_nop 1
	v_addc_co_u32_e32 v215, vcc, 0, v215, vcc
	global_load_dwordx4 v[216:219], v[214:215], off offset:2048
	v_mad_i64_i32 v[222:223], s[20:21], v34, s0, v[36:37]
	v_lshl_add_u64 v[224:225], v[222:223], 0, s[70:71]
	v_add_co_u32_e32 v224, vcc, s23, v224
	s_nop 1
	v_addc_co_u32_e32 v225, vcc, 0, v225, vcc
	global_load_dwordx4 v[226:229], v[224:225], off
	global_load_dwordx4 v[230:233], v161, s[84:85] offset:2064
	global_load_dwordx4 v[18:21], v161, s[84:85] offset:2048
	global_load_dwordx4 v[234:237], v161, s[86:87] offset:2064
	global_load_dwordx4 v[22:25], v161, s[86:87] offset:2048
	global_load_dwordx4 v[238:241], v161, s[36:37] offset:16
	global_load_dwordx4 v[26:29], v196, s[86:87]
	global_load_dwordx4 v[242:245], v161, s[38:39] offset:16
	global_load_dwordx4 v[246:249], v197, s[86:87] offset:2048
	s_waitcnt vmcnt(11)
	v_cndmask_b32_e64 v6, 0, v1, s[48:49]
	v_cndmask_b32_e64 v7, 0, v0, s[48:49]
	s_nop 0
	s_nop 0
	v_cndmask_b32_e64 v4, 0, v3, s[48:49]
	s_nop 0
	s_nop 0
	v_cndmask_b32_e64 v5, 0, v2, s[48:49]
	s_nop 0
	v_and_b32_e32 v13, 0xffff0000, v7
	v_lshlrev_b32_e32 v12, 16, v7
	v_and_b32_e32 v47, 0xffff0000, v6
	v_lshlrev_b32_e32 v46, 16, v6
	v_and_b32_e32 v43, 0xffff0000, v5
	v_lshlrev_b32_e32 v42, 16, v5
	v_and_b32_e32 v39, 0xffff0000, v4
	v_lshlrev_b32_e32 v38, 16, v4
	s_waitcnt vmcnt(10)
	v_cndmask_b32_e64 v10, 0, v209, s[54:55]
	v_cndmask_b32_e64 v11, 0, v208, s[54:55]
	s_nop 0
	s_nop 0
	v_cndmask_b32_e64 v8, 0, v211, s[54:55]
	s_nop 0
	s_nop 0
	v_cndmask_b32_e64 v9, 0, v210, s[54:55]
	s_nop 0
	v_and_b32_e32 v17, 0xffff0000, v11
	v_lshlrev_b32_e32 v16, 16, v11
	v_and_b32_e32 v49, 0xffff0000, v10
	v_lshlrev_b32_e32 v48, 16, v10
	v_and_b32_e32 v45, 0xffff0000, v9
	v_lshlrev_b32_e32 v44, 16, v9
	v_and_b32_e32 v41, 0xffff0000, v8
	v_lshlrev_b32_e32 v40, 16, v8
	s_waitcnt vmcnt(9)
	v_cndmask_b32_e64 v52, 0, v217, s[58:59]
	v_cndmask_b32_e64 v30, 0, v216, s[58:59]
	s_nop 0
	s_nop 0
	s_nop 0
	v_cndmask_b32_e64 v50, 0, v219, s[58:59]
	s_nop 0
	s_nop 0
	v_cndmask_b32_e64 v51, 0, v218, s[58:59]
	s_nop 0
	s_nop 0
	s_nop 0
	s_nop 0
	s_nop 0
	s_nop 0
	s_waitcnt vmcnt(5)
	v_pk_fma_f32 v[4:5], v[234:235], v[42:43], v[230:231]
	s_waitcnt vmcnt(4)
	v_pk_fma_f32 v[18:19], v[22:23], v[12:13], v[18:19]
	s_nop 0
	s_nop 0
	v_pk_fma_f32 v[20:21], v[24:25], v[46:47], v[20:21]
	v_and_b32_e32 v25, 0xffff0000, v52
	v_lshlrev_b32_e32 v24, 16, v52
	v_and_b32_e32 v9, 0xffff0000, v51
	v_lshlrev_b32_e32 v8, 16, v51
	v_pk_fma_f32 v[6:7], v[236:237], v[38:39], v[232:233]
	v_and_b32_e32 v10, 0xffff0000, v229
	v_lshlrev_b32_e32 v11, 16, v229
	s_waitcnt vmcnt(3)
	v_pk_fma_f32 v[4:5], v[238:239], v[44:45], v[4:5]
	s_waitcnt vmcnt(2)
	v_pk_fma_f32 v[22:23], v[26:27], v[16:17], v[18:19]
	v_and_b32_e32 v27, 0xffff0000, v30
	v_lshlrev_b32_e32 v26, 16, v30
	s_nop 0
	s_nop 0
	v_pk_fma_f32 v[20:21], v[28:29], v[48:49], v[20:21]
	v_pk_fma_f32 v[6:7], v[240:241], v[40:41], v[6:7]
	s_waitcnt vmcnt(1)
	v_pk_fma_f32 v[4:5], v[242:243], v[8:9], v[4:5]
	s_waitcnt vmcnt(0)
	v_pk_fma_f32 v[22:23], v[246:247], v[26:27], v[22:23]
	ds_read_u16 v27, v101 offset:1536
	ds_read_u16 v31, v101 offset:4608
	v_and_b32_e32 v30, 0xffff0000, v226
	v_lshlrev_b32_e32 v0, 16, v226
	v_mul_f32_e32 v26, 0xbfb8aa3b, v0
	s_waitcnt lgkmcnt(1)
	v_lshlrev_b32_e32 v54, 16, v27
	v_mul_f32_e32 v27, 0xbfb8aa3b, v30
	v_exp_f32_e32 v26, v26
	v_exp_f32_e32 v27, v27
	s_waitcnt lgkmcnt(0)
	v_lshlrev_b32_e32 v55, 16, v31
	v_pk_mul_f32 v[22:23], v[22:23], v[54:55]
	v_pk_fma_f32 v[20:21], v[248:249], v[24:25], v[20:21]
	v_pk_add_f32 v[26:27], v[26:27], 1.0 op_sel_hi:[1,0]
	v_and_b32_e32 v16, 0xffff0000, v228
	v_div_scale_f32 v31, s[20:21], v27, v27, v30
	v_rcp_f32_e32 v53, v31
	v_lshlrev_b32_e32 v2, 16, v228
	v_mul_f32_e32 v8, 0xbfb8aa3b, v2
	v_exp_f32_e32 v8, v8
	v_fma_f32 v54, -v31, v53, 1.0
	v_fmac_f32_e32 v53, v54, v53
	v_div_scale_f32 v54, vcc, v30, v27, v30
	v_mul_f32_e32 v55, v54, v53
	v_fma_f32 v56, -v31, v55, v54
	v_fmac_f32_e32 v55, v56, v53
	v_fma_f32 v31, -v31, v55, v54
	v_div_fmas_f32 v31, v31, v53, v55
	v_div_fixup_f32 v27, v31, v27, v30
	v_div_scale_f32 v30, s[20:21], v26, v26, v0
	v_rcp_f32_e32 v31, v30
	s_nop 0
	v_fma_f32 v53, -v30, v31, 1.0
	v_fmac_f32_e32 v31, v53, v31
	v_div_scale_f32 v53, vcc, v0, v26, v0
	v_mul_f32_e32 v54, v53, v31
	v_fma_f32 v55, -v30, v54, v53
	v_fmac_f32_e32 v54, v55, v31
	v_fma_f32 v30, -v30, v54, v53
	v_div_fmas_f32 v30, v30, v31, v54
	v_div_fixup_f32 v26, v30, v26, v0
	v_pk_mul_f32 v[22:23], v[26:27], v[22:23]
	v_and_b32_e32 v26, 0xffff0000, v227
	v_lshlrev_b32_e32 v27, 16, v227
	ds_read_u16 v1, v101 offset:7680
	ds_read_u16 v24, v101 offset:10752
	v_mul_f32_e32 v0, 0xbfb8aa3b, v27
	v_exp_f32_e32 v0, v0
	ds_read_u16 v9, v101 offset:13824
	ds_read_u16 v12, v101 offset:16896
	s_waitcnt lgkmcnt(2)
	v_lshlrev_b32_e32 v25, 16, v24
	v_lshlrev_b32_e32 v24, 16, v1
	v_mul_f32_e32 v1, 0xbfb8aa3b, v26
	v_exp_f32_e32 v1, v1
	v_pk_mul_f32 v[20:21], v[20:21], v[24:25]
	s_waitcnt lgkmcnt(0)
	v_lshlrev_b32_e32 v13, 16, v12
	v_lshlrev_b32_e32 v12, 16, v9
	v_pk_add_f32 v[0:1], v[0:1], 1.0 op_sel_hi:[1,0]
	v_mul_f32_e32 v9, 0xbfb8aa3b, v16
	v_div_scale_f32 v24, s[20:21], v1, v1, v26
	v_rcp_f32_e32 v25, v24
	v_exp_f32_e32 v9, v9
	v_pk_mul_f32 v[4:5], v[4:5], v[12:13]
	v_fma_f32 v28, -v24, v25, 1.0
	v_fmac_f32_e32 v25, v28, v25
	v_div_scale_f32 v28, vcc, v26, v1, v26
	v_mul_f32_e32 v29, v28, v25
	v_fma_f32 v30, -v24, v29, v28
	v_fmac_f32_e32 v29, v30, v25
	v_fma_f32 v24, -v24, v29, v28
	v_div_fmas_f32 v24, v24, v25, v29
	v_div_fixup_f32 v1, v24, v1, v26
	v_div_scale_f32 v24, s[20:21], v0, v0, v27
	v_rcp_f32_e32 v25, v24
	v_pk_add_f32 v[8:9], v[8:9], 1.0 op_sel_hi:[1,0]
	v_fma_f32 v26, -v24, v25, 1.0
	v_fmac_f32_e32 v25, v26, v25
	v_div_scale_f32 v26, vcc, v27, v0, v27
	v_div_scale_f32 v12, s[20:21], v9, v9, v16
	v_mul_f32_e32 v28, v26, v25
	v_rcp_f32_e32 v13, v12
	v_fma_f32 v29, -v24, v28, v26
	v_fmac_f32_e32 v28, v29, v25
	v_fma_f32 v24, -v24, v28, v26
	v_div_fmas_f32 v24, v24, v25, v28
	v_fma_f32 v17, -v12, v13, 1.0
	v_div_fixup_f32 v0, v24, v0, v27
	v_fmac_f32_e32 v13, v17, v13
	v_div_scale_f32 v17, vcc, v16, v9, v16
	v_pk_mul_f32 v[0:1], v[0:1], v[20:21]
	v_mul_f32_e32 v20, v17, v13
	v_fma_f32 v21, -v12, v20, v17
	v_fmac_f32_e32 v20, v21, v13
	v_fma_f32 v12, -v12, v20, v17
	v_div_fmas_f32 v12, v12, v13, v20
	v_div_fixup_f32 v9, v12, v9, v16
	v_div_scale_f32 v12, s[20:21], v8, v8, v2
	v_rcp_f32_e32 v13, v12
	s_nop 0
	v_fma_f32 v16, -v12, v13, 1.0
	v_fmac_f32_e32 v13, v16, v13
	v_div_scale_f32 v16, vcc, v2, v8, v2
	v_mul_f32_e32 v17, v16, v13
	v_fma_f32 v20, -v12, v17, v16
	v_fmac_f32_e32 v17, v20, v13
	v_fma_f32 v12, -v12, v17, v16
	v_div_fmas_f32 v12, v12, v13, v17
	v_div_fixup_f32 v8, v12, v8, v2
	v_pk_mul_f32 v[4:5], v[8:9], v[4:5]
	v_and_b32_e32 v9, 0xffff0000, v50
	v_lshlrev_b32_e32 v8, 16, v50
	v_pk_fma_f32 v[6:7], v[244:245], v[8:9], v[6:7]
	ds_read_u16 v3, v101 offset:19968
	ds_read_u16 v8, v101 offset:23040
	v_mul_f32_e32 v2, 0xbfb8aa3b, v11
	v_exp_f32_e32 v2, v2
	s_waitcnt lgkmcnt(0)
	v_lshlrev_b32_e32 v9, 16, v8
	v_lshlrev_b32_e32 v8, 16, v3
	v_mul_f32_e32 v3, 0xbfb8aa3b, v10
	v_exp_f32_e32 v3, v3
	v_pk_mul_f32 v[6:7], v[6:7], v[8:9]
	v_pk_add_f32 v[2:3], v[2:3], 1.0 op_sel_hi:[1,0]
	s_nop 0
	v_div_scale_f32 v8, s[20:21], v3, v3, v10
	v_rcp_f32_e32 v9, v8
	s_nop 0
	v_fma_f32 v12, -v8, v9, 1.0
	v_fmac_f32_e32 v9, v12, v9
	v_div_scale_f32 v12, vcc, v10, v3, v10
	v_mul_f32_e32 v13, v12, v9
	v_fma_f32 v14, -v8, v13, v12
	v_fmac_f32_e32 v13, v14, v9
	v_fma_f32 v8, -v8, v13, v12
	v_div_fmas_f32 v8, v8, v9, v13
	v_div_fixup_f32 v3, v8, v3, v10
	v_div_scale_f32 v8, s[20:21], v2, v2, v11
	v_rcp_f32_e32 v9, v8
	s_nop 0
	v_fma_f32 v10, -v8, v9, 1.0
	v_fmac_f32_e32 v9, v10, v9
	v_div_scale_f32 v10, vcc, v11, v2, v11
	v_mul_f32_e32 v12, v10, v9
	v_fma_f32 v13, -v8, v12, v10
	v_fmac_f32_e32 v12, v13, v9
	v_fma_f32 v8, -v8, v12, v10
	v_div_fmas_f32 v8, v8, v9, v12
	v_div_fixup_f32 v2, v8, v2, v11
	v_pk_mul_f32 v[2:3], v[2:3], v[6:7]
	v_cvt_pk_bf16_f32 v4, v4, v5
	v_cvt_pk_bf16_f32 v2, v2, v3
	v_mov_b32_e32 v3, v2
	v_mov_b32_e32 v2, v4
	v_lshlrev_b64 v[4:5], 12, v[34:35]
	v_lshl_add_u64 v[4:5], s[30:31], 0, v[4:5]
	v_bfe_u32 v12, v23, 16, 1
	v_bfe_u32 v13, v22, 16, 1
	v_lshl_add_u64 v[4:5], v[4:5], 0, s[70:71]
	v_add3_u32 v13, v22, v13, s94
	v_add3_u32 v12, v23, v12, s94
	v_cvt_pk_bf16_f32 v0, v0, v1
	v_add_co_u32_e32 v4, vcc, s22, v4
	v_mov_b32_e32 v1, v0
	v_perm_b32 v0, v12, v13, s95
	v_addc_co_u32_e32 v5, vcc, 0, v5, vcc
	global_store_dwordx4 v[4:5], v[0:3], off offset:3072
	v_mov_b32_e32 v15, v241
	v_mov_b32_e32 v18, v244
	v_mov_b32_e32 v19, v245
	v_mov_b32_e32 v32, v248
	v_mov_b32_e32 v33, v249
	v_add_u32_e32 v34, s19, v120
	v_ashrrev_i32_e32 v35, 31, v34
	v_lshl_add_u64 v[0:1], v[102:103], 0, s[70:71]
	v_add_co_u32_e32 v0, vcc, s3, v0
	s_nop 1
	v_addc_co_u32_e32 v1, vcc, 0, v1, vcc
	global_load_dwordx4 v[0:3], v[0:1], off offset:2048
	s_waitcnt vmcnt(1)
	v_lshl_add_u64 v[206:207], v[104:105], 0, s[70:71]
	v_add_co_u32_e32 v206, vcc, s3, v206
	s_nop 1
	v_addc_co_u32_e32 v207, vcc, 0, v207, vcc
	global_load_dwordx4 v[208:211], v[206:207], off offset:2048
	v_lshl_add_u64 v[214:215], v[106:107], 0, s[70:71]
	v_add_co_u32_e32 v214, vcc, s3, v214
	s_nop 1
	v_addc_co_u32_e32 v215, vcc, 0, v215, vcc
	global_load_dwordx4 v[216:219], v[214:215], off offset:2048
	v_mad_i64_i32 v[222:223], s[20:21], v34, s0, v[36:37]
	v_lshl_add_u64 v[224:225], v[222:223], 0, s[70:71]
	v_add_co_u32_e32 v224, vcc, s23, v224
	s_nop 1
	v_addc_co_u32_e32 v225, vcc, 0, v225, vcc
	global_load_dwordx4 v[226:229], v[224:225], off
	global_load_dwordx4 v[230:233], v161, s[84:85] offset:2064
	global_load_dwordx4 v[18:21], v161, s[84:85] offset:2048
	global_load_dwordx4 v[234:237], v161, s[86:87] offset:2064
	global_load_dwordx4 v[22:25], v161, s[86:87] offset:2048
	global_load_dwordx4 v[238:241], v161, s[36:37] offset:16
	global_load_dwordx4 v[26:29], v196, s[86:87]
	global_load_dwordx4 v[242:245], v161, s[38:39] offset:16
	global_load_dwordx4 v[246:249], v197, s[86:87] offset:2048
	s_waitcnt vmcnt(11)
	v_cndmask_b32_e64 v6, 0, v1, s[44:45]
	v_cndmask_b32_e64 v7, 0, v0, s[44:45]
	s_nop 0
	s_nop 0
	v_cndmask_b32_e64 v4, 0, v3, s[44:45]
	s_nop 0
	s_nop 0
	v_cndmask_b32_e64 v5, 0, v2, s[44:45]
	s_nop 0
	v_and_b32_e32 v13, 0xffff0000, v7
	v_lshlrev_b32_e32 v12, 16, v7
	v_and_b32_e32 v45, 0xffff0000, v6
	v_lshlrev_b32_e32 v44, 16, v6
	v_and_b32_e32 v41, 0xffff0000, v5
	v_lshlrev_b32_e32 v40, 16, v5
	s_waitcnt vmcnt(10)
	v_cndmask_b32_e64 v10, 0, v209, s[46:47]
	v_cndmask_b32_e64 v11, 0, v208, s[46:47]
	s_nop 0
	s_nop 0
	v_cndmask_b32_e64 v8, 0, v211, s[46:47]
	s_nop 0
	s_nop 0
	v_cndmask_b32_e64 v9, 0, v210, s[46:47]
	s_nop 0
	v_and_b32_e32 v17, 0xffff0000, v11
	v_lshlrev_b32_e32 v16, 16, v11
	v_and_b32_e32 v47, 0xffff0000, v10
	v_lshlrev_b32_e32 v46, 16, v10
	v_and_b32_e32 v43, 0xffff0000, v9
	v_lshlrev_b32_e32 v42, 16, v9
	v_and_b32_e32 v39, 0xffff0000, v8
	v_lshlrev_b32_e32 v38, 16, v8
	s_waitcnt vmcnt(9)
	v_cndmask_b32_e64 v50, 0, v217, s[52:53]
	v_cndmask_b32_e64 v30, 0, v216, s[52:53]
	s_nop 0
	s_nop 0
	s_nop 0
	v_cndmask_b32_e64 v48, 0, v219, s[52:53]
	s_nop 0
	s_nop 0
	v_cndmask_b32_e64 v49, 0, v218, s[52:53]
	s_nop 0
	v_and_b32_e32 v37, 0xffff0000, v4
	v_lshlrev_b32_e32 v36, 16, v4
	s_nop 0
	s_nop 0
	s_nop 0
	s_nop 0
	s_waitcnt vmcnt(5)
	v_pk_fma_f32 v[4:5], v[234:235], v[40:41], v[230:231]
	s_waitcnt vmcnt(4)
	v_pk_fma_f32 v[18:19], v[22:23], v[12:13], v[18:19]
	s_nop 0
	s_nop 0
	v_pk_fma_f32 v[20:21], v[24:25], v[44:45], v[20:21]
	v_and_b32_e32 v25, 0xffff0000, v50
	v_lshlrev_b32_e32 v24, 16, v50
	v_and_b32_e32 v9, 0xffff0000, v49
	v_lshlrev_b32_e32 v8, 16, v49
	v_pk_fma_f32 v[6:7], v[236:237], v[36:37], v[232:233]
	s_waitcnt vmcnt(3)
	v_pk_fma_f32 v[4:5], v[238:239], v[42:43], v[4:5]
	s_waitcnt vmcnt(2)
	v_pk_fma_f32 v[22:23], v[26:27], v[16:17], v[18:19]
	v_and_b32_e32 v27, 0xffff0000, v30
	v_lshlrev_b32_e32 v26, 16, v30
	s_nop 0
	s_nop 0
	v_pk_fma_f32 v[20:21], v[28:29], v[46:47], v[20:21]
	v_pk_fma_f32 v[6:7], v[240:241], v[38:39], v[6:7]
	s_waitcnt vmcnt(1)
	v_pk_fma_f32 v[4:5], v[242:243], v[8:9], v[4:5]
	s_waitcnt vmcnt(0)
	v_pk_fma_f32 v[22:23], v[246:247], v[26:27], v[22:23]
	ds_read_u16 v27, v101 offset:2048
	ds_read_u16 v31, v101 offset:5120
	v_and_b32_e32 v30, 0xffff0000, v226
	v_lshlrev_b32_e32 v0, 16, v226
	v_mul_f32_e32 v26, 0xbfb8aa3b, v0
	s_waitcnt lgkmcnt(1)
	v_lshlrev_b32_e32 v52, 16, v27
	v_mul_f32_e32 v27, 0xbfb8aa3b, v30
	v_exp_f32_e32 v26, v26
	v_exp_f32_e32 v27, v27
	s_waitcnt lgkmcnt(0)
	v_lshlrev_b32_e32 v53, 16, v31
	v_pk_mul_f32 v[22:23], v[22:23], v[52:53]
	v_pk_fma_f32 v[20:21], v[248:249], v[24:25], v[20:21]
	v_pk_add_f32 v[26:27], v[26:27], 1.0 op_sel_hi:[1,0]
	v_and_b32_e32 v25, 0xffff0000, v227
	v_div_scale_f32 v31, s[20:21], v27, v27, v30
	v_rcp_f32_e32 v51, v31
	v_lshlrev_b32_e32 v24, 16, v227
	v_and_b32_e32 v16, 0xffff0000, v228
	v_lshlrev_b32_e32 v2, 16, v228
	v_fma_f32 v52, -v31, v51, 1.0
	v_fmac_f32_e32 v51, v52, v51
	v_div_scale_f32 v52, vcc, v30, v27, v30
	v_mul_f32_e32 v53, v52, v51
	v_fma_f32 v54, -v31, v53, v52
	v_fmac_f32_e32 v53, v54, v51
	v_fma_f32 v31, -v31, v53, v52
	v_div_fmas_f32 v31, v31, v51, v53
	v_div_fixup_f32 v27, v31, v27, v30
	v_div_scale_f32 v30, s[20:21], v26, v26, v0
	v_rcp_f32_e32 v31, v30
	v_mul_f32_e32 v8, 0xbfb8aa3b, v2
	v_exp_f32_e32 v8, v8
	v_fma_f32 v51, -v30, v31, 1.0
	v_fmac_f32_e32 v31, v51, v31
	v_div_scale_f32 v51, vcc, v0, v26, v0
	v_mul_f32_e32 v52, v51, v31
	v_fma_f32 v53, -v30, v52, v51
	v_fmac_f32_e32 v52, v53, v31
	v_fma_f32 v30, -v30, v52, v51
	v_div_fmas_f32 v30, v30, v31, v52
	v_div_fixup_f32 v26, v30, v26, v0
	v_pk_mul_f32 v[22:23], v[26:27], v[22:23]
	ds_read_u16 v1, v101 offset:8192
	ds_read_u16 v26, v101 offset:11264
	v_mul_f32_e32 v0, 0xbfb8aa3b, v24
	v_exp_f32_e32 v0, v0
	ds_read_u16 v9, v101 offset:14336
	ds_read_u16 v12, v101 offset:17408
	s_waitcnt lgkmcnt(2)
	v_lshlrev_b32_e32 v27, 16, v26
	v_lshlrev_b32_e32 v26, 16, v1
	v_mul_f32_e32 v1, 0xbfb8aa3b, v25
	v_exp_f32_e32 v1, v1
	v_pk_mul_f32 v[20:21], v[20:21], v[26:27]
	s_waitcnt lgkmcnt(0)
	v_lshlrev_b32_e32 v13, 16, v12
	v_lshlrev_b32_e32 v12, 16, v9
	v_pk_add_f32 v[0:1], v[0:1], 1.0 op_sel_hi:[1,0]
	v_mul_f32_e32 v9, 0xbfb8aa3b, v16
	v_div_scale_f32 v26, s[20:21], v1, v1, v25
	v_rcp_f32_e32 v27, v26
	v_exp_f32_e32 v9, v9
	v_pk_mul_f32 v[4:5], v[4:5], v[12:13]
	v_fma_f32 v28, -v26, v27, 1.0
	v_fmac_f32_e32 v27, v28, v27
	v_div_scale_f32 v28, vcc, v25, v1, v25
	v_mul_f32_e32 v29, v28, v27
	v_fma_f32 v30, -v26, v29, v28
	v_fmac_f32_e32 v29, v30, v27
	v_fma_f32 v26, -v26, v29, v28
	v_div_fmas_f32 v26, v26, v27, v29
	v_div_fixup_f32 v1, v26, v1, v25
	v_div_scale_f32 v25, s[20:21], v0, v0, v24
	v_rcp_f32_e32 v26, v25
	v_pk_add_f32 v[8:9], v[8:9], 1.0 op_sel_hi:[1,0]
	v_fma_f32 v27, -v25, v26, 1.0
	v_fmac_f32_e32 v26, v27, v26
	v_div_scale_f32 v27, vcc, v24, v0, v24
	v_div_scale_f32 v12, s[20:21], v9, v9, v16
	v_mul_f32_e32 v28, v27, v26
	v_rcp_f32_e32 v13, v12
	v_fma_f32 v29, -v25, v28, v27
	v_fmac_f32_e32 v28, v29, v26
	v_fma_f32 v25, -v25, v28, v27
	v_div_fmas_f32 v25, v25, v26, v28
	v_fma_f32 v17, -v12, v13, 1.0
	v_div_fixup_f32 v0, v25, v0, v24
	v_fmac_f32_e32 v13, v17, v13
	v_div_scale_f32 v17, vcc, v16, v9, v16
	v_pk_mul_f32 v[0:1], v[0:1], v[20:21]
	v_mul_f32_e32 v20, v17, v13
	v_fma_f32 v21, -v12, v20, v17
	v_fmac_f32_e32 v20, v21, v13
	v_fma_f32 v12, -v12, v20, v17
	v_div_fmas_f32 v12, v12, v13, v20
	v_div_fixup_f32 v9, v12, v9, v16
	v_div_scale_f32 v12, s[20:21], v8, v8, v2
	v_rcp_f32_e32 v13, v12
	s_nop 0
	v_fma_f32 v16, -v12, v13, 1.0
	v_fmac_f32_e32 v13, v16, v13
	v_div_scale_f32 v16, vcc, v2, v8, v2
	v_mul_f32_e32 v17, v16, v13
	v_fma_f32 v20, -v12, v17, v16
	v_fmac_f32_e32 v17, v20, v13
	v_fma_f32 v12, -v12, v17, v16
	v_div_fmas_f32 v12, v12, v13, v17
	v_div_fixup_f32 v8, v12, v8, v2
	v_pk_mul_f32 v[4:5], v[8:9], v[4:5]
	v_and_b32_e32 v9, 0xffff0000, v48
	v_lshlrev_b32_e32 v8, 16, v48
	v_pk_fma_f32 v[6:7], v[244:245], v[8:9], v[6:7]
	v_and_b32_e32 v9, 0xffff0000, v229
	v_lshlrev_b32_e32 v8, 16, v229
	ds_read_u16 v3, v101 offset:20480
	ds_read_u16 v10, v101 offset:23552
	v_mul_f32_e32 v2, 0xbfb8aa3b, v8
	v_exp_f32_e32 v2, v2
	s_waitcnt lgkmcnt(0)
	v_lshlrev_b32_e32 v11, 16, v10
	v_lshlrev_b32_e32 v10, 16, v3
	v_mul_f32_e32 v3, 0xbfb8aa3b, v9
	v_exp_f32_e32 v3, v3
	v_pk_mul_f32 v[6:7], v[6:7], v[10:11]
	v_pk_add_f32 v[2:3], v[2:3], 1.0 op_sel_hi:[1,0]
	s_nop 0
	v_div_scale_f32 v10, s[20:21], v3, v3, v9
	v_rcp_f32_e32 v11, v10
	s_nop 0
	v_fma_f32 v12, -v10, v11, 1.0
	v_fmac_f32_e32 v11, v12, v11
	v_div_scale_f32 v12, vcc, v9, v3, v9
	v_mul_f32_e32 v13, v12, v11
	v_fma_f32 v14, -v10, v13, v12
	v_fmac_f32_e32 v13, v14, v11
	v_fma_f32 v10, -v10, v13, v12
	v_div_fmas_f32 v10, v10, v11, v13
	v_div_fixup_f32 v3, v10, v3, v9
	v_div_scale_f32 v9, s[20:21], v2, v2, v8
	v_rcp_f32_e32 v10, v9
	s_nop 0
	v_fma_f32 v11, -v9, v10, 1.0
	v_fmac_f32_e32 v10, v11, v10
	v_div_scale_f32 v11, vcc, v8, v2, v8
	v_mul_f32_e32 v12, v11, v10
	v_fma_f32 v13, -v9, v12, v11
	v_fmac_f32_e32 v12, v13, v10
	v_fma_f32 v9, -v9, v12, v11
	v_div_fmas_f32 v9, v9, v10, v12
	v_div_fixup_f32 v2, v9, v2, v8
	v_pk_mul_f32 v[2:3], v[2:3], v[6:7]
	v_cvt_pk_bf16_f32 v4, v4, v5
	v_cvt_pk_bf16_f32 v2, v2, v3
	v_mov_b32_e32 v3, v2
	v_mov_b32_e32 v2, v4
	v_lshlrev_b64 v[4:5], 12, v[34:35]
	v_lshl_add_u64 v[4:5], s[30:31], 0, v[4:5]
	v_bfe_u32 v12, v23, 16, 1
	v_bfe_u32 v13, v22, 16, 1
	v_lshl_add_u64 v[4:5], v[4:5], 0, s[70:71]
	v_add3_u32 v13, v22, v13, s94
	v_add3_u32 v12, v23, v12, s94
	v_cvt_pk_bf16_f32 v0, v0, v1
	v_add_co_u32_e32 v4, vcc, 0xcc00000, v4
	v_mov_b32_e32 v1, v0
	v_perm_b32 v0, v12, v13, s95
	v_addc_co_u32_e32 v5, vcc, 0, v5, vcc
	global_store_dwordx4 v[4:5], v[0:3], off offset:3072
	v_mov_b32_e32 v15, v241
	v_mov_b32_e32 v18, v244
	v_mov_b32_e32 v19, v245
	v_mov_b32_e32 v32, v248
	v_mov_b32_e32 v33, v249
	s_barrier
